# lever 1: pre-phase row loop no longer drains the next row's prefetch mid-row (counted waits moved to the consumer)
# speedup vs baseline: 1.0167x; 1.0167x over previous
.LBB0_233:
	s_or_b64 exec, exec, s[16:17]
	v_mul_f32_e32 v88, v29, v29
	v_fmac_f32_e32 v88, v28, v28
	v_fmac_f32_e32 v88, v30, v30
	v_fmac_f32_e32 v88, v31, v31
	v_fmac_f32_e32 v88, v24, v24
	v_fmac_f32_e32 v88, v25, v25
	v_fmac_f32_e32 v88, v26, v26
	v_fmac_f32_e32 v88, v27, v27
	v_fmac_f32_e32 v88, v20, v20
	v_fmac_f32_e32 v88, v21, v21
	v_fmac_f32_e32 v88, v22, v22
	v_fmac_f32_e32 v88, v23, v23
	v_pk_mul_f32 v[100:101], v[16:17], v[16:17]
	v_pk_mul_f32 v[98:99], v[18:19], v[18:19]
	v_add_f32_e32 v88, v100, v88
	v_add_f32_e32 v88, v101, v88
	v_add_f32_e32 v88, v98, v88
	v_add_f32_e32 v88, v99, v88
	ds_bpermute_b32 v98, v89, v88
	s_and_b64 s[2:3], exec, s[2:3]
	s_or_b64 s[8:9], s[2:3], s[8:9]
	v_lshl_add_u64 v[66:67], v[66:67], 0, s[6:7]
	s_waitcnt lgkmcnt(0)
	v_add_f32_e32 v88, v88, v98
	ds_bpermute_b32 v98, v92, v88
	s_waitcnt lgkmcnt(0)
	v_add_f32_e32 v88, v88, v98
	ds_bpermute_b32 v98, v93, v88
	s_waitcnt lgkmcnt(0)
	v_add_f32_e32 v88, v88, v98
	ds_bpermute_b32 v98, v94, v88
	s_waitcnt lgkmcnt(0)
	v_add_f32_e32 v88, v88, v98
	ds_bpermute_b32 v98, v95, v88
	s_waitcnt lgkmcnt(0)
	v_add_f32_e32 v88, v88, v98
	ds_bpermute_b32 v98, v96, v88
	s_waitcnt lgkmcnt(0)
	v_add_f32_e32 v88, v88, v98
	v_fmamk_f32 v88, v88, 0x3a800000, v90
	v_mul_f32_e32 v98, 0x4b800000, v88
	v_cmp_gt_f32_e32 vcc, s25, v88
	s_nop 1
	v_cndmask_b32_e32 v88, v88, v98, vcc
	v_rsq_f32_e32 v88, v88
	s_nop 0
	v_mul_f32_e32 v98, 0x45800000, v88
	v_cndmask_b32_e32 v88, v88, v98, vcc
	v_pk_mul_f32 v[28:29], v[28:29], v[88:89] op_sel_hi:[1,0]
	v_pk_mul_f32 v[30:31], v[30:31], v[88:89] op_sel_hi:[1,0]
	v_pk_mul_f32 v[24:25], v[24:25], v[88:89] op_sel_hi:[1,0]
	v_pk_mul_f32 v[26:27], v[26:27], v[88:89] op_sel_hi:[1,0]
	v_pk_mul_f32 v[16:17], v[16:17], v[88:89] op_sel_hi:[1,0]
	v_pk_mul_f32 v[98:99], v[18:19], v[88:89] op_sel_hi:[1,0]
	s_nop 0
	v_pk_mul_f32 v[18:19], v[8:9], v[28:29]
	v_pk_mul_f32 v[28:29], v[10:11], v[30:31]
	s_nop 0
	v_pk_mul_f32 v[24:25], v[12:13], v[24:25]
	v_pk_mul_f32 v[26:27], v[14:15], v[26:27]
	v_pk_mul_f32 v[16:17], v[4:5], v[16:17]
	v_pk_fma_f32 v[18:19], v[80:81], v[18:19], v[36:37]
	v_pk_fma_f32 v[28:29], v[78:79], v[28:29], v[38:39]
	v_pk_fma_f32 v[24:25], v[76:77], v[24:25], v[32:33]
	v_pk_fma_f32 v[26:27], v[74:75], v[26:27], v[34:35]
	v_pk_mul_f32 v[20:21], v[20:21], v[88:89] op_sel_hi:[1,0]
	v_pk_mul_f32 v[22:23], v[22:23], v[88:89] op_sel_hi:[1,0]
	v_pk_fma_f32 v[30:31], v[82:83], v[16:17], v[40:41]
	v_cvt_pk_bf16_f32 v16, v18, v19
	v_cvt_pk_bf16_f32 v17, v28, v29
	v_cvt_pk_bf16_f32 v18, v24, v25
	v_cvt_pk_bf16_f32 v19, v26, v27
	v_pk_mul_f32 v[20:21], v[0:1], v[20:21]
	v_pk_mul_f32 v[22:23], v[2:3], v[22:23]
	global_store_dwordx4 v[70:71], v[16:19], off
	v_pk_fma_f32 v[20:21], v[72:73], v[20:21], v[44:45]
	v_pk_fma_f32 v[22:23], v[84:85], v[22:23], v[46:47]
	v_pk_mul_f32 v[16:17], v[6:7], v[98:99]
	v_cvt_pk_bf16_f32 v18, v30, v31
	v_pk_fma_f32 v[24:25], v[86:87], v[16:17], v[42:43]
	v_cvt_pk_bf16_f32 v16, v20, v21
	v_cvt_pk_bf16_f32 v17, v22, v23
	v_cvt_pk_bf16_f32 v19, v24, v25
	global_store_dwordx4 v[70:71], v[16:19], off offset:1024
	s_waitcnt vmcnt(2)
	v_mov_b64_e32 v[20:21], v[60:61]
	v_mov_b64_e32 v[24:25], v[48:49]
	v_mov_b64_e32 v[16:17], v[56:57]
	v_mov_b64_e32 v[28:29], v[52:53]
	v_lshl_add_u64 v[70:71], v[70:71], 0, s[14:15]
	v_mov_b64_e32 v[18:19], v[58:59]
	v_mov_b64_e32 v[22:23], v[62:63]
	v_mov_b64_e32 v[26:27], v[50:51]
	v_mov_b64_e32 v[30:31], v[54:55]
	v_mov_b32_e32 v88, v97
	s_andn2_b64 exec, exec, s[8:9]
	s_cbranch_execz .LBB0_238

.LBB0_236:
	s_or_b64 exec, exec, s[16:17]
	v_min_i32_e32 v88, 0x8000, v88
	v_ashrrev_i32_e32 v88, 13, v88
	v_cmp_ne_u32_e32 vcc, v88, v91
	s_and_saveexec_b64 s[16:17], vcc
	s_cbranch_execz .LBB0_233
	v_mul_hi_i32_i24_e32 v33, 0x3000, v88
	v_mul_i32_i24_e32 v32, 0x3000, v88
	v_lshl_add_u64 v[76:77], v[68:69], 0, v[32:33]
	v_add_co_u32_e32 v78, vcc, 0x1000, v76
	v_lshl_add_u64 v[32:33], v[76:77], 0, s[10:11]
	s_nop 0
	v_addc_co_u32_e32 v79, vcc, 0, v77, vcc
	global_load_dwordx4 v[72:75], v[78:79], off
	global_load_dwordx4 v[82:85], v[32:33], off offset:16
	v_lshl_add_u64 v[80:81], v[76:77], 0, s[12:13]
	global_load_dwordx4 v[98:101], v[78:79], off offset:2048
	global_load_dwordx4 v[102:105], v[80:81], off offset:16
	global_load_dwordx4 v[36:39], v[76:77], off
	global_load_dwordx4 v[32:35], v[76:77], off offset:16
	global_load_dwordx4 v[44:47], v[76:77], off offset:2048
	global_load_dwordx4 v[40:43], v[76:77], off offset:2064
	v_mov_b32_e32 v91, v88
	s_waitcnt vmcnt(0)
	v_pk_add_f32 v[86:87], v[104:105], 1.0 op_sel_hi:[1,0]
	v_pk_add_f32 v[80:81], v[72:73], 1.0 op_sel_hi:[1,0]
	v_pk_add_f32 v[78:79], v[74:75], 1.0 op_sel_hi:[1,0]
	v_pk_add_f32 v[76:77], v[82:83], 1.0 op_sel_hi:[1,0]
	v_pk_add_f32 v[74:75], v[84:85], 1.0 op_sel_hi:[1,0]
	v_pk_add_f32 v[72:73], v[98:99], 1.0 op_sel_hi:[1,0]
	v_pk_add_f32 v[84:85], v[100:101], 1.0 op_sel_hi:[1,0]
	v_pk_add_f32 v[82:83], v[102:103], 1.0 op_sel_hi:[1,0]
	s_branch .LBB0_233
